# FoX key-norm bound computed once per (b,h) by a distributed pre-pass at gMLP start (atomic max table in g_ctl) instead of per-unit K pass
# speedup vs baseline: 1.0285x; 1.0136x over previous
.LBB0_543:
	s_load_dwordx2 s[10:11], s[0:1], 0
	s_waitcnt lgkmcnt(0)
	s_and_b64 vcc, exec, s[38:39]
	s_load_dwordx2 s[10:11], s[0:1], 8
	s_waitcnt lgkmcnt(0)
	s_nop 0
	s_load_dwordx2 s[10:11], s[0:1], 16
	s_waitcnt lgkmcnt(0)
	s_nop 0
	s_load_dwordx2 s[10:11], s[0:1], 24
	s_waitcnt lgkmcnt(0)
	s_load_dwordx2 s[34:35], s[0:1], 32
	s_waitcnt lgkmcnt(0)
	s_load_dwordx2 s[28:29], s[0:1], 40
	s_waitcnt lgkmcnt(0)
	s_load_dwordx2 s[30:31], s[0:1], 48
	s_waitcnt lgkmcnt(0)
	s_load_dwordx2 s[22:23], s[0:1], 56
	s_waitcnt lgkmcnt(0)
	s_nop 0
	s_load_dwordx2 s[10:11], s[0:1], 64
	s_waitcnt lgkmcnt(0)
	s_nop 0
	s_load_dwordx2 s[10:11], s[0:1], 0x48
	s_waitcnt lgkmcnt(0)
	s_nop 0
	s_load_dwordx2 s[10:11], s[0:1], 0x50
	s_waitcnt lgkmcnt(0)
	s_nop 0
	s_load_dwordx2 s[10:11], s[0:1], 0x58
	s_waitcnt lgkmcnt(0)
	s_nop 0
	s_load_dwordx2 s[10:11], s[0:1], 0x60
	s_waitcnt lgkmcnt(0)
	s_load_dwordx2 s[26:27], s[0:1], 0x68
	s_waitcnt lgkmcnt(0)
	s_cbranch_vccnz .LBB0_554
	v_readlane_b32 s100, v252, 9
	s_nop 3
	s_lshr_b32 s101, s100, 3
	s_and_b32 s100, s100, 7
	s_lshr_b32 s2, s101, 3
	s_and_b32 s3, s101, 7
	s_lshl_b32 s2, s2, 12
	s_lshl_b32 s20, s100, 9
	s_add_i32 s2, s2, s20
	s_mul_i32 s20, s2, 0x1e00
	s_lshl_b32 s3, s3, 7
	s_add_u32 s20, s20, s3
	s_add_u32 s20, s20, 0x7001200
	s_add_u32 s2, s26, s20
	s_addc_u32 s3, s27, 0
	v_lshrrev_b32_e32 v32, 3, v184
	v_mul_u32_u24_e32 v32, 0x1e00, v32
	v_and_b32_e32 v33, 7, v184
	v_lshl_add_u32 v32, v33, 4, v32
	global_load_dwordx4 v[36:39], v32, s[2:3]
	v_add_u32_e32 v33, 0x78000, v32
	global_load_dwordx4 v[40:43], v33, s[2:3]
	v_add_u32_e32 v33, 0xf0000, v32
	global_load_dwordx4 v[44:47], v33, s[2:3]
	v_add_u32_e32 v33, 0x168000, v32
	global_load_dwordx4 v[48:51], v33, s[2:3]
	v_add_u32_e32 v33, 0x1e0000, v32
	global_load_dwordx4 v[52:55], v33, s[2:3]
	v_add_u32_e32 v33, 0x258000, v32
	global_load_dwordx4 v[56:59], v33, s[2:3]
	v_add_u32_e32 v33, 0x2d0000, v32
	global_load_dwordx4 v[60:63], v33, s[2:3]
	v_add_u32_e32 v33, 0x348000, v32
	global_load_dwordx4 v[64:67], v33, s[2:3]
	v_mov_b32_e32 v70, 0
	s_waitcnt vmcnt(7)
	v_lshlrev_b32_e32 v72, 16, v36
	v_and_b32_e32 v73, 0xffff0000, v36
	v_mul_f32_e32 v71, v72, v72
	v_fmac_f32_e32 v71, v73, v73
	v_lshlrev_b32_e32 v72, 16, v37
	v_and_b32_e32 v73, 0xffff0000, v37
	v_fmac_f32_e32 v71, v72, v72
	v_fmac_f32_e32 v71, v73, v73
	v_lshlrev_b32_e32 v72, 16, v38
	v_and_b32_e32 v73, 0xffff0000, v38
	v_fmac_f32_e32 v71, v72, v72
	v_fmac_f32_e32 v71, v73, v73
	v_lshlrev_b32_e32 v72, 16, v39
	v_and_b32_e32 v73, 0xffff0000, v39
	v_fmac_f32_e32 v71, v72, v72
	v_fmac_f32_e32 v71, v73, v73
	v_max_f32_e32 v70, v70, v71
	s_waitcnt vmcnt(6)
	v_lshlrev_b32_e32 v72, 16, v40
	v_and_b32_e32 v73, 0xffff0000, v40
	v_mul_f32_e32 v71, v72, v72
	v_fmac_f32_e32 v71, v73, v73
	v_lshlrev_b32_e32 v72, 16, v41
	v_and_b32_e32 v73, 0xffff0000, v41
	v_fmac_f32_e32 v71, v72, v72
	v_fmac_f32_e32 v71, v73, v73
	v_lshlrev_b32_e32 v72, 16, v42
	v_and_b32_e32 v73, 0xffff0000, v42
	v_fmac_f32_e32 v71, v72, v72
	v_fmac_f32_e32 v71, v73, v73
	v_lshlrev_b32_e32 v72, 16, v43
	v_and_b32_e32 v73, 0xffff0000, v43
	v_fmac_f32_e32 v71, v72, v72
	v_fmac_f32_e32 v71, v73, v73
	v_max_f32_e32 v70, v70, v71
	s_waitcnt vmcnt(5)
	v_lshlrev_b32_e32 v72, 16, v44
	v_and_b32_e32 v73, 0xffff0000, v44
	v_mul_f32_e32 v71, v72, v72
	v_fmac_f32_e32 v71, v73, v73
	v_lshlrev_b32_e32 v72, 16, v45
	v_and_b32_e32 v73, 0xffff0000, v45
	v_fmac_f32_e32 v71, v72, v72
	v_fmac_f32_e32 v71, v73, v73
	v_lshlrev_b32_e32 v72, 16, v46
	v_and_b32_e32 v73, 0xffff0000, v46
	v_fmac_f32_e32 v71, v72, v72
	v_fmac_f32_e32 v71, v73, v73
	v_lshlrev_b32_e32 v72, 16, v47
	v_and_b32_e32 v73, 0xffff0000, v47
	v_fmac_f32_e32 v71, v72, v72
	v_fmac_f32_e32 v71, v73, v73
	v_max_f32_e32 v70, v70, v71
	s_waitcnt vmcnt(4)
	v_lshlrev_b32_e32 v72, 16, v48
	v_and_b32_e32 v73, 0xffff0000, v48
	v_mul_f32_e32 v71, v72, v72
	v_fmac_f32_e32 v71, v73, v73
	v_lshlrev_b32_e32 v72, 16, v49
	v_and_b32_e32 v73, 0xffff0000, v49
	v_fmac_f32_e32 v71, v72, v72
	v_fmac_f32_e32 v71, v73, v73
	v_lshlrev_b32_e32 v72, 16, v50
	v_and_b32_e32 v73, 0xffff0000, v50
	v_fmac_f32_e32 v71, v72, v72
	v_fmac_f32_e32 v71, v73, v73
	v_lshlrev_b32_e32 v72, 16, v51
	v_and_b32_e32 v73, 0xffff0000, v51
	v_fmac_f32_e32 v71, v72, v72
	v_fmac_f32_e32 v71, v73, v73
	v_max_f32_e32 v70, v70, v71
	s_waitcnt vmcnt(3)
	v_lshlrev_b32_e32 v72, 16, v52
	v_and_b32_e32 v73, 0xffff0000, v52
	v_mul_f32_e32 v71, v72, v72
	v_fmac_f32_e32 v71, v73, v73
	v_lshlrev_b32_e32 v72, 16, v53
	v_and_b32_e32 v73, 0xffff0000, v53
	v_fmac_f32_e32 v71, v72, v72
	v_fmac_f32_e32 v71, v73, v73
	v_lshlrev_b32_e32 v72, 16, v54
	v_and_b32_e32 v73, 0xffff0000, v54
	v_fmac_f32_e32 v71, v72, v72
	v_fmac_f32_e32 v71, v73, v73
	v_lshlrev_b32_e32 v72, 16, v55
	v_and_b32_e32 v73, 0xffff0000, v55
	v_fmac_f32_e32 v71, v72, v72
	v_fmac_f32_e32 v71, v73, v73
	v_max_f32_e32 v70, v70, v71
	s_waitcnt vmcnt(2)
	v_lshlrev_b32_e32 v72, 16, v56
	v_and_b32_e32 v73, 0xffff0000, v56
	v_mul_f32_e32 v71, v72, v72
	v_fmac_f32_e32 v71, v73, v73
	v_lshlrev_b32_e32 v72, 16, v57
	v_and_b32_e32 v73, 0xffff0000, v57
	v_fmac_f32_e32 v71, v72, v72
	v_fmac_f32_e32 v71, v73, v73
	v_lshlrev_b32_e32 v72, 16, v58
	v_and_b32_e32 v73, 0xffff0000, v58
	v_fmac_f32_e32 v71, v72, v72
	v_fmac_f32_e32 v71, v73, v73
	v_lshlrev_b32_e32 v72, 16, v59
	v_and_b32_e32 v73, 0xffff0000, v59
	v_fmac_f32_e32 v71, v72, v72
	v_fmac_f32_e32 v71, v73, v73
	v_max_f32_e32 v70, v70, v71
	s_waitcnt vmcnt(1)
	v_lshlrev_b32_e32 v72, 16, v60
	v_and_b32_e32 v73, 0xffff0000, v60
	v_mul_f32_e32 v71, v72, v72
	v_fmac_f32_e32 v71, v73, v73
	v_lshlrev_b32_e32 v72, 16, v61
	v_and_b32_e32 v73, 0xffff0000, v61
	v_fmac_f32_e32 v71, v72, v72
	v_fmac_f32_e32 v71, v73, v73
	v_lshlrev_b32_e32 v72, 16, v62
	v_and_b32_e32 v73, 0xffff0000, v62
	v_fmac_f32_e32 v71, v72, v72
	v_fmac_f32_e32 v71, v73, v73
	v_lshlrev_b32_e32 v72, 16, v63
	v_and_b32_e32 v73, 0xffff0000, v63
	v_fmac_f32_e32 v71, v72, v72
	v_fmac_f32_e32 v71, v73, v73
	v_max_f32_e32 v70, v70, v71
	s_waitcnt vmcnt(0)
	v_lshlrev_b32_e32 v72, 16, v64
	v_and_b32_e32 v73, 0xffff0000, v64
	v_mul_f32_e32 v71, v72, v72
	v_fmac_f32_e32 v71, v73, v73
	v_lshlrev_b32_e32 v72, 16, v65
	v_and_b32_e32 v73, 0xffff0000, v65
	v_fmac_f32_e32 v71, v72, v72
	v_fmac_f32_e32 v71, v73, v73
	v_lshlrev_b32_e32 v72, 16, v66
	v_and_b32_e32 v73, 0xffff0000, v66
	v_fmac_f32_e32 v71, v72, v72
	v_fmac_f32_e32 v71, v73, v73
	v_lshlrev_b32_e32 v72, 16, v67
	v_and_b32_e32 v73, 0xffff0000, v67
	v_fmac_f32_e32 v71, v72, v72
	v_fmac_f32_e32 v71, v73, v73
	v_max_f32_e32 v70, v70, v71
	v_and_b32_e32 v74, 63, v184
	v_lshlrev_b32_e32 v74, 2, v74
	v_xor_b32_e32 v75, 32, v74
	ds_bpermute_b32 v72, v75, v70
	s_waitcnt lgkmcnt(0)
	v_max_f32_e32 v70, v70, v72
	v_xor_b32_e32 v75, 64, v74
	ds_bpermute_b32 v72, v75, v70
	s_waitcnt lgkmcnt(0)
	v_max_f32_e32 v70, v70, v72
	v_xor_b32_e32 v75, 128, v74
	ds_bpermute_b32 v72, v75, v70
	s_waitcnt lgkmcnt(0)
	v_max_f32_e32 v70, v70, v72
	s_lshl_b32 s2, s101, 6
	s_lshl_b32 s3, s16, 11
	s_add_i32 s2, s2, s3
	s_getpc_b64 s[100:101]
	s_add_u32 s100, s100, g_ctl@rel32@lo+51204
	s_addc_u32 s101, s101, g_ctl@rel32@hi+51212
	s_add_u32 s100, s100, s2
	s_addc_u32 s101, s101, 0
	s_mov_b64 exec, 0xff
	global_atomic_umax v72, v74, v70, s[100:101] sc0
	s_waitcnt vmcnt(0)
	s_mov_b64 exec, 1
	global_atomic_add v191, v193, s[100:101] offset:32
	s_mov_b64 exec, -1
	s_add_u32 s24, s26, 0x4000000
	s_addc_u32 s25, s27, 0
	v_readlane_b32 s2, v252, 24
	s_add_u32 s26, s26, 0x7000000
	v_readlane_b32 s3, v252, 25
	s_addc_u32 s27, s27, 0
	s_lshl_b64 s[10:11], s[2:3], 2
	s_add_u32 s18, s34, s10
	s_addc_u32 s19, s35, s11
	s_add_u32 s28, s28, s10
	s_addc_u32 s29, s29, s11
	s_lshl_b32 s10, s16, 2
	s_add_u32 s30, s30, 16
	v_readlane_b32 s2, v252, 9
	s_addc_u32 s31, s31, 0
	s_lshl_b32 s11, s16, 9
	s_mov_b32 s12, s2
	s_mov_b32 s13, s2
	v_readlane_b32 s3, v252, 10
	s_branch .LBB0_546

.LBB0_574:
	v_readfirstlane_b32 s2, v165
	s_nop 3
	s_lshr_b32 s2, s2, 6
	s_lshl_b32 s2, s2, 5
	s_lshl_b32 s3, s48, 8
	s_add_i32 s2, s2, s3
	s_add_i32 s20, s2, -32
	s_lshl_b32 s42, s20, 2
	s_mul_i32 s20, s20, 0x1e00
	s_add_u32 s20, s20, 0x7001200
	s_add_u32 s2, s28, s20
	s_addc_u32 s3, s29, 0
	v_and_b32_e32 v60, 31, v165
	v_mul_u32_u24_e32 v60, 0x1e00, v60
	v_bfe_u32 v61, v165, 5, 1
	v_lshl_add_u32 v60, v61, 4, v60
	v_add_u32_e32 v61, s42, v179
	global_load_dwordx4 v[64:67], v60, s[2:3] offset:0
	global_load_dwordx4 v[68:71], v60, s[2:3] offset:32
	global_load_dwordx4 v[72:75], v60, s[2:3] offset:64
	global_load_dwordx4 v[76:79], v60, s[2:3] offset:96
	ds_read_b128 v[32:35], v61
	ds_read_b128 v[36:39], v61 offset:32
	ds_read_b128 v[40:43], v61 offset:64
	ds_read_b128 v[44:47], v61 offset:96
	s_waitcnt lgkmcnt(0)
	s_waitcnt vmcnt(3)
	v_mfma_f32_32x32x16_bf16 v[32:47], v[64:67], v[96:99], v[32:47]
	s_waitcnt vmcnt(2)
	v_mfma_f32_32x32x16_bf16 v[32:47], v[68:71], v[100:103], v[32:47]
	s_waitcnt vmcnt(1)
	v_mfma_f32_32x32x16_bf16 v[32:47], v[72:75], v[104:107], v[32:47]
	s_waitcnt vmcnt(0)
	v_mfma_f32_32x32x16_bf16 v[32:47], v[76:79], v[108:111], v[32:47]
	s_nop 11
	v_max3_f32 v222, v32, v33, v34
	v_max3_f32 v222, v222, v35, v36
	v_max3_f32 v222, v222, v37, v38
	v_max3_f32 v222, v222, v39, v40
	v_max3_f32 v222, v222, v41, v42
	v_max3_f32 v222, v222, v43, v44
	v_max3_f32 v222, v222, v45, v46
	v_max_f32_e32 v222, v222, v47
	ds_bpermute_b32 v183, v180, v222
	s_waitcnt lgkmcnt(0)
	v_max_f32_e32 v183, v183, v183
	v_max_f32_e32 v182, v222, v183
	v_sub_f32_e32 v182, v182, v161
	v_add_f32_e32 v255, 0xc2200000, v182
	s_sub_u32 s2, s26, s10
	s_lshr_b32 s2, s2, 14
	s_lshl_b32 s2, s2, 6
	s_lshl_b32 s3, s16, 11
	s_add_i32 s2, s2, s3
	s_getpc_b64 s[100:101]
	s_add_u32 s100, s100, g_ctl@rel32@lo+51204
	s_addc_u32 s101, s101, g_ctl@rel32@hi+51212
	s_add_u32 s100, s100, s2
	s_addc_u32 s101, s101, 0
	s_mov_b32 s20, 0
.Lfox_km_spin:
	global_load_dword v210, v191, s[100:101] offset:32 sc1
	s_waitcnt vmcnt(0)
	v_readfirstlane_b32 s2, v210
	s_nop 3
	s_cmp_ge_u32 s2, 64
	s_cbranch_scc1 .Lfox_km_ready
	s_sleep 2
	s_add_i32 s20, s20, 1
	s_cmp_lt_u32 s20, 0x20000
	s_cbranch_scc1 .Lfox_km_spin
	v_mov_b32_e32 v254, 0x7f800000
	s_branch .Lfox_kpass_done
.Lfox_km_ready:
	v_and_b32_e32 v214, 63, v165
	v_lshlrev_b32_e32 v214, 2, v214
	v_and_b32_e32 v215, 28, v214
	s_nop 0
	global_load_dword v210, v215, s[100:101] sc1
	s_waitcnt vmcnt(0)
	v_xor_b32_e32 v215, 4, v214
	ds_bpermute_b32 v216, v215, v210
	s_waitcnt lgkmcnt(0)
	v_add_f32_e32 v210, v210, v216
	v_xor_b32_e32 v215, 8, v214
	ds_bpermute_b32 v216, v215, v210
	s_waitcnt lgkmcnt(0)
	v_add_f32_e32 v210, v210, v216
	v_xor_b32_e32 v215, 16, v214
	ds_bpermute_b32 v216, v215, v210
	s_waitcnt lgkmcnt(0)
	v_add_f32_e32 v210, v210, v216
	v_mov_b32_e32 v254, v210
	s_branch .Lfox_kpass_done
	s_mov_b64 s[2:3], 0x7001200
	v_lshl_add_u64 v[202:203], v[158:159], 0, s[2:3]
	s_mov_b64 s[2:3], 0x78000
	v_lshl_add_u64 v[204:205], v[202:203], 0, s[2:3]
	v_mov_b32_e32 v210, 0
	s_lshl_b32 s20, s48, 1
	s_add_i32 s100, s20, 1
	s_add_i32 s20, s48, 1
	s_lshr_b32 s20, s20, 1
	s_mov_b32 s101, 0
	s_mov_b32 s3, 0
	s_min_u32 s2, s101, s100
	s_mul_i32 s2, s2, 0xf0000
	s_add_i32 s101, s101, 1
	v_lshl_add_u64 v[206:207], v[202:203], 0, s[2:3]
	v_lshl_add_u64 v[208:209], v[204:205], 0, s[2:3]
	global_load_dwordx4 v[32:35], v[206:207], off
	global_load_dwordx4 v[36:39], v[208:209], off
	s_min_u32 s2, s101, s100
	s_mul_i32 s2, s2, 0xf0000
	s_add_i32 s101, s101, 1
	v_lshl_add_u64 v[206:207], v[202:203], 0, s[2:3]
	v_lshl_add_u64 v[208:209], v[204:205], 0, s[2:3]
	global_load_dwordx4 v[40:43], v[206:207], off
	global_load_dwordx4 v[44:47], v[208:209], off
	s_min_u32 s2, s101, s100
	s_mul_i32 s2, s2, 0xf0000
	s_add_i32 s101, s101, 1
	v_lshl_add_u64 v[206:207], v[202:203], 0, s[2:3]
	v_lshl_add_u64 v[208:209], v[204:205], 0, s[2:3]
	global_load_dwordx4 v[48:51], v[206:207], off
	global_load_dwordx4 v[52:55], v[208:209], off
	s_min_u32 s2, s101, s100
	s_mul_i32 s2, s2, 0xf0000
	s_add_i32 s101, s101, 1
	v_lshl_add_u64 v[206:207], v[202:203], 0, s[2:3]
	v_lshl_add_u64 v[208:209], v[204:205], 0, s[2:3]
	global_load_dwordx4 v[56:59], v[206:207], off
	global_load_dwordx4 v[60:63], v[208:209], off
	s_min_u32 s2, s101, s100
	s_mul_i32 s2, s2, 0xf0000
	s_add_i32 s101, s101, 1
	v_lshl_add_u64 v[206:207], v[202:203], 0, s[2:3]
	v_lshl_add_u64 v[208:209], v[204:205], 0, s[2:3]
	global_load_dwordx4 v[64:67], v[206:207], off
	global_load_dwordx4 v[68:71], v[208:209], off
	s_min_u32 s2, s101, s100
	s_mul_i32 s2, s2, 0xf0000
	s_add_i32 s101, s101, 1
	v_lshl_add_u64 v[206:207], v[202:203], 0, s[2:3]
	v_lshl_add_u64 v[208:209], v[204:205], 0, s[2:3]
	global_load_dwordx4 v[72:75], v[206:207], off
	global_load_dwordx4 v[76:79], v[208:209], off
	s_min_u32 s2, s101, s100
	s_mul_i32 s2, s2, 0xf0000
	s_add_i32 s101, s101, 1
	v_lshl_add_u64 v[206:207], v[202:203], 0, s[2:3]
	v_lshl_add_u64 v[208:209], v[204:205], 0, s[2:3]
	global_load_dwordx4 v[80:83], v[206:207], off
	global_load_dwordx4 v[84:87], v[208:209], off
	s_min_u32 s2, s101, s100
	s_mul_i32 s2, s2, 0xf0000
	s_add_i32 s101, s101, 1
	v_lshl_add_u64 v[206:207], v[202:203], 0, s[2:3]
	v_lshl_add_u64 v[208:209], v[204:205], 0, s[2:3]
	global_load_dwordx4 v[88:91], v[206:207], off
	global_load_dwordx4 v[92:95], v[208:209], off
